# barriers 1-3: agent acquires dropped (every read of P1/P2/P3 is a first touch of the launch, no line is shared between writers, caches clean at dispatch)
# speedup vs baseline: 1.0305x; 1.0081x over previous
.LBB0_113:
	s_or_b64 exec, exec, s[4:5]
	v_cvt_f32_u32_e32 v4, v2
	s_waitcnt vmcnt(0)
	v_readfirstlane_b32 s3, v3
	v_sub_u32_e32 v3, 0, v2
	v_rcp_iflag_f32_e32 v4, v4
	v_add_u32_e32 v5, s3, v1
	v_mul_f32_e32 v4, 0x4f7ffffe, v4
	v_cvt_u32_f32_e32 v4, v4
	v_mul_lo_u32 v1, v3, v4
	v_mul_hi_u32 v1, v4, v1
	v_add_u32_e32 v1, v4, v1
	v_mul_hi_u32 v1, v5, v1
	v_mul_lo_u32 v3, v1, v2
	v_sub_u32_e32 v3, v5, v3
	v_add_u32_e32 v4, 1, v1
	v_cmp_ge_u32_e32 vcc, v3, v2
	s_nop 1
	v_cndmask_b32_e32 v1, v1, v4, vcc
	v_sub_u32_e32 v4, v3, v2
	v_cndmask_b32_e32 v3, v3, v4, vcc
	v_add_u32_e32 v4, 1, v1
	v_cmp_ge_u32_e32 vcc, v3, v2
	v_add_u32_e32 v3, 1, v5
	s_nop 0
	v_cndmask_b32_e32 v1, v1, v4, vcc
	v_mul_lo_u32 v4, v2, v1
	v_add_u32_e32 v2, v4, v2
	v_cmp_ne_u32_e32 vcc, v3, v2
	s_and_saveexec_b64 s[4:5], vcc
	s_xor_b64 s[4:5], exec, s[4:5]
	s_cbranch_execz .LBB0_127
	s_waitcnt lgkmcnt(0)
	v_mov_b32_e32 v0, 0
	s_nop 0
	global_load_dword v2, v0, s[20:21] sc1
	s_waitcnt vmcnt(0)
	v_cmp_eq_u32_e32 vcc, v2, v1
	s_and_saveexec_b64 s[6:7], vcc
	s_cbranch_execz .LBB0_126
	s_mov_b32 s3, 1
	s_mov_b64 s[8:9], 0
	s_branch .LBB0_117

.LBB0_127:
	s_andn2_saveexec_b64 s[4:5], s[4:5]
	s_cbranch_execz .LBB0_147
	s_mov_b64 s[4:5], exec
	buffer_wbl2 sc1
	s_waitcnt vmcnt(0) lgkmcnt(0)
	s_nop 0
	v_add_u32_e32 v4, 1, v1
	v_mul_lo_u32 v4, v4, v0
	v_readlane_b32 s4, v254, 50
	v_readlane_b32 s5, v254, 51
	v_mov_b32_e32 v2, 0
	v_mov_b32_e32 v3, 1
	s_mov_b32 s3, 0
	s_nop 4
	global_atomic_add v2, v3, s[4:5]

.LBB0_398:
	s_or_b64 exec, exec, s[4:5]
	v_cvt_f32_u32_e32 v4, v2
	s_waitcnt vmcnt(0)
	v_readfirstlane_b32 s4, v3
	v_sub_u32_e32 v3, 0, v2
	v_rcp_iflag_f32_e32 v4, v4
	v_add_u32_e32 v5, s4, v1
	v_mul_f32_e32 v4, 0x4f7ffffe, v4
	v_cvt_u32_f32_e32 v4, v4
	v_mul_lo_u32 v1, v3, v4
	v_mul_hi_u32 v1, v4, v1
	v_add_u32_e32 v1, v4, v1
	v_mul_hi_u32 v1, v5, v1
	v_mul_lo_u32 v3, v1, v2
	v_sub_u32_e32 v3, v5, v3
	v_add_u32_e32 v4, 1, v1
	v_cmp_ge_u32_e32 vcc, v3, v2
	s_nop 1
	v_cndmask_b32_e32 v1, v1, v4, vcc
	v_sub_u32_e32 v4, v3, v2
	v_cndmask_b32_e32 v3, v3, v4, vcc
	v_add_u32_e32 v4, 1, v1
	v_cmp_ge_u32_e32 vcc, v3, v2
	v_add_u32_e32 v3, 1, v5
	s_nop 0
	v_cndmask_b32_e32 v1, v1, v4, vcc
	v_mul_lo_u32 v4, v2, v1
	v_add_u32_e32 v2, v4, v2
	v_cmp_ne_u32_e32 vcc, v3, v2
	s_and_saveexec_b64 s[4:5], vcc
	s_xor_b64 s[4:5], exec, s[4:5]
	s_cbranch_execz .LBB0_412
	v_readlane_b32 s6, v255, 0
	s_waitcnt lgkmcnt(0)
	v_mov_b32_e32 v0, 0
	v_readlane_b32 s7, v255, 1
	s_nop 4
	s_nop 0
	global_load_dword v2, v0, s[6:7] sc1
	s_waitcnt vmcnt(0)
	v_cmp_eq_u32_e32 vcc, v2, v1
	s_and_saveexec_b64 s[6:7], vcc
	s_cbranch_execz .LBB0_411
	s_mov_b32 s22, 1
	s_mov_b64 s[12:13], 0
	s_branch .LBB0_402

.LBB0_412:
	s_andn2_saveexec_b64 s[4:5], s[4:5]
	s_cbranch_execz .LBB0_432
	s_mov_b64 s[6:7], exec
	buffer_wbl2 sc1
	s_waitcnt vmcnt(0) lgkmcnt(0)
	s_nop 0
	v_add_u32_e32 v4, 1, v1
	v_mul_lo_u32 v4, v4, v0
	v_readlane_b32 s6, v254, 50
	v_readlane_b32 s7, v254, 51
	v_mov_b32_e32 v2, 0
	v_mov_b32_e32 v3, 1
	s_mov_b32 s24, 0
	s_nop 4
	global_atomic_add v2, v3, s[6:7]

.LBB0_545:
	s_or_b64 exec, exec, s[4:5]
	v_cvt_f32_u32_e32 v4, v2
	s_waitcnt vmcnt(0)
	v_readfirstlane_b32 s4, v3
	v_sub_u32_e32 v3, 0, v2
	v_rcp_iflag_f32_e32 v4, v4
	v_add_u32_e32 v5, s4, v1
	v_mul_f32_e32 v4, 0x4f7ffffe, v4
	v_cvt_u32_f32_e32 v4, v4
	v_mul_lo_u32 v1, v3, v4
	v_mul_hi_u32 v1, v4, v1
	v_add_u32_e32 v1, v4, v1
	v_mul_hi_u32 v1, v5, v1
	v_mul_lo_u32 v3, v1, v2
	v_sub_u32_e32 v3, v5, v3
	v_add_u32_e32 v4, 1, v1
	v_cmp_ge_u32_e32 vcc, v3, v2
	s_nop 1
	v_cndmask_b32_e32 v1, v1, v4, vcc
	v_sub_u32_e32 v4, v3, v2
	v_cndmask_b32_e32 v3, v3, v4, vcc
	v_add_u32_e32 v4, 1, v1
	v_cmp_ge_u32_e32 vcc, v3, v2
	v_add_u32_e32 v3, 1, v5
	s_nop 0
	v_cndmask_b32_e32 v1, v1, v4, vcc
	v_mul_lo_u32 v4, v2, v1
	v_add_u32_e32 v2, v4, v2
	v_cmp_ne_u32_e32 vcc, v3, v2
	s_and_saveexec_b64 s[4:5], vcc
	s_xor_b64 s[4:5], exec, s[4:5]
	s_cbranch_execz .LBB0_559
	v_readlane_b32 s6, v255, 0
	s_waitcnt lgkmcnt(0)
	v_mov_b32_e32 v0, 0
	v_readlane_b32 s7, v255, 1
	s_nop 4
	s_nop 0
	global_load_dword v2, v0, s[6:7] sc1
	s_waitcnt vmcnt(0)
	v_cmp_eq_u32_e32 vcc, v2, v1
	s_and_saveexec_b64 s[6:7], vcc
	s_cbranch_execz .LBB0_558
	s_mov_b32 s28, 1
	s_mov_b64 s[10:11], 0
	s_branch .LBB0_549

.LBB0_559:
	s_andn2_saveexec_b64 s[4:5], s[4:5]
	s_cbranch_execz .LBB0_579
	s_mov_b64 s[6:7], exec
	buffer_wbl2 sc1
	s_waitcnt vmcnt(0) lgkmcnt(0)
	s_nop 0
	v_add_u32_e32 v4, 1, v1
	v_mul_lo_u32 v4, v4, v0
	v_readlane_b32 s6, v254, 50
	v_readlane_b32 s7, v254, 51
	v_mov_b32_e32 v2, 0
	v_mov_b32_e32 v3, 1
	s_mov_b32 s30, 0
	s_nop 4
	global_atomic_add v2, v3, s[6:7]
